# v47 + P3 tg/tm temp accesses as global_load/store_dwordx2 instead of flat (address-space specialization, no lgkmcnt use)
# speedup vs baseline: 1.0076x; 1.0076x over previous
; __device__ __forceinline__ u32x2 pk4(f32x4 v) { u32x2 w; w.x = pk2(v[0], v[1]); w.y = pk2(v[2], v[3]); return w; }
;     __device__ __forceinline__ void operator()(const f32x4 (&acc)[2][2][4][2], const Unit& u, int wr, int wc, int fr, int fq) const {
;         const int mode = u.mode;
;         const int loff = (wr * 4 + wc) * (32 * 64) + fq * 16 + fr;
;         u32x2* tg = tb_ + loff; u32x2* tm = tb_ + 32 * 512 + loff;
;         asm volatile("" : "+v"(tg), "+v"(tm));
;         if (mode == 0) {
; #pragma unroll
;             for (int ai = 0; ai < 2; ++ai)
; #pragma unroll
;                 for (int bj = 0; bj < 2; ++bj)
; #pragma unroll
;                     for (int m = 0; m < 4; ++m)
; #pragma unroll
;                         for (int n = 0; n < 2; ++n) { const int idx = ((ai * 2 + bj) * 4 + m) * 2 + n; f32x4 a = acc[ai][bj][m][n], sg;
; #pragma unroll
;                             for (int e = 0; e < 4; ++e) sg[e] = __builtin_amdgcn_rcpf(1.0f + __builtin_amdgcn_exp2f((-1.4426950408889634f / 32.0f) * a[e]));
;                             tg[idx * 64] = pk4(sg); if (n) asm volatile("" ::: "memory"); }
;         } else {
;             const int row0 = u.pm * BM + wr * 64 + fr, col0 = u.pn * BM + wc * 32 + 8 * fq;
; #pragma unroll
;             for (int ai = 0; ai < 2; ++ai) {
;                 u32x2 g[16], t[16];
; #pragma unroll
;                 for (int k = 0; k < 16; ++k) { g[k] = tg[(ai * 16 + k) * 64]; if (mode != 1) t[k] = tm[(ai * 16 + k) * 64]; }
.LBB0_542:
	v_mbcnt_lo_u32_b32 v219, -1, 0
	v_mbcnt_hi_u32_b32 v219, -1, v219
	s_cmp_lg_u32 s70, 0
	v_and_b32_e32 v128, 15, v219
	v_and_b32_e32 v134, -16, v219
	v_or_b32_e32 v135, s25, v128
	v_add_u32_e32 v134, v135, v134
	v_ashrrev_i32_e32 v135, 31, v134
	v_lshlrev_b64 v[136:137], 3, v[134:135]
	v_lshl_add_u64 v[134:135], s[40:41], 0, v[136:137]
	v_lshl_add_u64 v[136:137], s[42:43], 0, v[136:137]
	s_cbranch_scc0 .LBB0_677
	global_load_dwordx2 v[144:145], v[134:135], off
	s_cmp_lg_u32 s70, 1
	s_cselect_b64 s[10:11], -1, 0
	s_cmp_eq_u32 s70, 1
	s_cbranch_scc1 .LBB0_545
	global_load_dwordx2 v[172:173], v[136:137], off
.LBB0_545:
	global_load_dwordx2 v[142:143], v[134:135], off offset:512
	v_cndmask_b32_e64 v138, 0, 1, s[10:11]
	v_cmp_ne_u32_e64 s[8:9], 1, v138
	s_andn2_b64 vcc, exec, s[10:11]
	s_cbranch_vccz .LBB0_678
	global_load_dwordx2 v[200:201], v[134:135], off offset:1024
	s_and_b64 vcc, exec, s[8:9]
	s_cbranch_vccz .LBB0_679
.LBB0_547:
	global_load_dwordx2 v[196:197], v[134:135], off offset:1536
	s_and_b64 vcc, exec, s[8:9]
	s_cbranch_vccz .LBB0_680
.LBB0_548:
	global_load_dwordx2 v[198:199], v[134:135], off offset:2048
	s_and_b64 vcc, exec, s[8:9]
	s_cbranch_vccz .LBB0_681
.LBB0_549:
	global_load_dwordx2 v[194:195], v[134:135], off offset:2560
	s_and_b64 vcc, exec, s[8:9]
	s_cbranch_vccz .LBB0_682
.LBB0_550:
	global_load_dwordx2 v[192:193], v[134:135], off offset:3072
	s_and_b64 vcc, exec, s[8:9]
	s_cbranch_vccz .LBB0_683
.LBB0_551:
	global_load_dwordx2 v[190:191], v[134:135], off offset:3584
	s_and_b64 vcc, exec, s[8:9]
	s_cbranch_vccnz .LBB0_553
.LBB0_552:
	global_load_dwordx2 v[158:159], v[136:137], off offset:3584
.LBB0_553:
	v_add_co_u32_e32 v138, vcc, 0x1000, v134
	s_nop 1
	v_addc_co_u32_e32 v139, vcc, 0, v135, vcc
	global_load_dwordx2 v[186:187], v[138:139], off
	s_and_b64 vcc, exec, s[8:9]
	s_cbranch_vccnz .LBB0_555
	v_add_co_u32_e32 v138, vcc, 0x1000, v136
	s_nop 1
	v_addc_co_u32_e32 v139, vcc, 0, v137, vcc
	global_load_dwordx2 v[154:155], v[138:139], off
.LBB0_555:
	v_add_co_u32_e32 v138, vcc, 0x1000, v134
	s_nop 1
	v_addc_co_u32_e32 v139, vcc, 0, v135, vcc
	global_load_dwordx2 v[188:189], v[138:139], off offset:512
	s_and_b64 vcc, exec, s[8:9]
	s_cbranch_vccnz .LBB0_557
	v_add_co_u32_e32 v138, vcc, 0x1000, v136
	s_nop 1
	v_addc_co_u32_e32 v139, vcc, 0, v137, vcc
	global_load_dwordx2 v[156:157], v[138:139], off offset:512
.LBB0_557:
	v_add_co_u32_e32 v138, vcc, 0x1000, v134
	s_nop 1
	v_addc_co_u32_e32 v139, vcc, 0, v135, vcc
	global_load_dwordx2 v[182:183], v[138:139], off offset:1024
	s_and_b64 vcc, exec, s[8:9]
	s_cbranch_vccnz .LBB0_559
	v_add_co_u32_e32 v138, vcc, 0x1000, v136
	s_nop 1
	v_addc_co_u32_e32 v139, vcc, 0, v137, vcc
	global_load_dwordx2 v[150:151], v[138:139], off offset:1024
.LBB0_559:
	v_add_co_u32_e32 v138, vcc, 0x1000, v134
	s_nop 1
	v_addc_co_u32_e32 v139, vcc, 0, v135, vcc
	global_load_dwordx2 v[184:185], v[138:139], off offset:1536
	s_and_b64 vcc, exec, s[8:9]
	s_cbranch_vccnz .LBB0_561
	v_add_co_u32_e32 v138, vcc, 0x1000, v136
	s_nop 1
	v_addc_co_u32_e32 v139, vcc, 0, v137, vcc
	global_load_dwordx2 v[152:153], v[138:139], off offset:1536
.LBB0_561:
	v_add_co_u32_e32 v138, vcc, 0x1000, v134
	s_nop 1
	v_addc_co_u32_e32 v139, vcc, 0, v135, vcc
	global_load_dwordx2 v[178:179], v[138:139], off offset:2048
	s_and_b64 vcc, exec, s[8:9]
	s_cbranch_vccnz .LBB0_563
	v_add_co_u32_e32 v138, vcc, 0x1000, v136
	s_nop 1
	v_addc_co_u32_e32 v139, vcc, 0, v137, vcc
	global_load_dwordx2 v[146:147], v[138:139], off offset:2048
.LBB0_563:
	v_add_co_u32_e32 v138, vcc, 0x1000, v134
	s_nop 1
	v_addc_co_u32_e32 v139, vcc, 0, v135, vcc
	global_load_dwordx2 v[180:181], v[138:139], off offset:2560
	s_and_b64 vcc, exec, s[8:9]
	s_cbranch_vccnz .LBB0_565
	v_add_co_u32_e32 v138, vcc, 0x1000, v136
	s_nop 1
	v_addc_co_u32_e32 v139, vcc, 0, v137, vcc
	global_load_dwordx2 v[148:149], v[138:139], off offset:2560
.LBB0_565:
	v_add_co_u32_e32 v138, vcc, 0x1000, v134
	s_nop 1
	v_addc_co_u32_e32 v139, vcc, 0, v135, vcc
	global_load_dwordx2 v[174:175], v[138:139], off offset:3072
	s_and_b64 vcc, exec, s[8:9]
	s_cbranch_vccnz .LBB0_567
	v_add_co_u32_e32 v138, vcc, 0x1000, v136
	s_nop 1
	v_addc_co_u32_e32 v139, vcc, 0, v137, vcc
	global_load_dwordx2 v[138:139], v[138:139], off offset:3072
.LBB0_567:
	v_add_co_u32_e32 v140, vcc, 0x1000, v134
	s_nop 1
	v_addc_co_u32_e32 v141, vcc, 0, v135, vcc
	global_load_dwordx2 v[176:177], v[140:141], off offset:3584
	s_and_b64 vcc, exec, s[8:9]
	s_cbranch_vccnz .LBB0_569
	v_add_co_u32_e32 v140, vcc, 0x1000, v136
	s_nop 1
	v_addc_co_u32_e32 v141, vcc, 0, v137, vcc
	global_load_dwordx2 v[140:141], v[140:141], off offset:3584

; __device__ __forceinline__ u32x2 pk4(f32x4 v) { u32x2 w; w.x = pk2(v[0], v[1]); w.y = pk2(v[2], v[3]); return w; }
;     __device__ __forceinline__ void operator()(const f32x4 (&acc)[2][2][4][2], const Unit& u, int wr, int wc, int fr, int fq) const {
;     ...
; #pragma unroll
;                 for (int bj = 0; bj < 2; ++bj)
; #pragma unroll
;                     for (int m = 0; m < 4; ++m) { const int k = (bj * 4 + m) * 2;
;                         f32x4 v0 = unpk4(g[k]) * (acc[ai][bj][m][0] * (1.0f / 512.0f)), v1 = unpk4(g[k + 1]) * (acc[ai][bj][m][1] * (1.0f / 512.0f));
;                         if (mode != 1) { v0 += unpk4(t[k]); v1 += unpk4(t[k + 1]); }
;                         if (mode != 3) { tm[(ai * 16 + k) * 64] = pk4(v0); tm[(ai * 16 + k + 1) * 64] = pk4(v1); }
.LBB0_571:
	s_cmp_lg_u32 s70, 3
	s_cselect_b64 s[66:67], -1, 0
	s_cmp_eq_u32 s70, 3
	s_mov_b64 s[10:11], -1
	s_cbranch_scc1 .LBB0_573
	v_cvt_pk_bf16_f32 v142, v204, v205
	v_cvt_pk_bf16_f32 v143, v202, v203
	global_store_dwordx2 v[136:137], v[142:143], off
	v_cvt_pk_bf16_f32 v142, v208, v209
	v_cvt_pk_bf16_f32 v143, v206, v207
	s_mov_b64 s[10:11], 0
	global_store_dwordx2 v[136:137], v[142:143], off offset:512

; __device__ __forceinline__ u32x2 pk4(f32x4 v) { u32x2 w; w.x = pk2(v[0], v[1]); w.y = pk2(v[2], v[3]); return w; }
;     __device__ __forceinline__ void operator()(const f32x4 (&acc)[2][2][4][2], const Unit& u, int wr, int wc, int fr, int fq) const {
;     ...
; #pragma unroll
;                 for (int bj = 0; bj < 2; ++bj)
; #pragma unroll
;                     for (int m = 0; m < 4; ++m) { const int k = (bj * 4 + m) * 2;
;                         f32x4 v0 = unpk4(g[k]) * (acc[ai][bj][m][0] * (1.0f / 512.0f)), v1 = unpk4(g[k + 1]) * (acc[ai][bj][m][1] * (1.0f / 512.0f));
;                         if (mode != 1) { v0 += unpk4(t[k]); v1 += unpk4(t[k + 1]); }
;                         if (mode != 3) { tm[(ai * 16 + k) * 64] = pk4(v0); tm[(ai * 16 + k + 1) * 64] = pk4(v1); }
.LBB0_577:
	v_cndmask_b32_e64 v128, 0, 1, s[66:67]
	v_cmp_ne_u32_e64 s[10:11], 1, v128
	s_andn2_b64 vcc, exec, s[66:67]
	s_mov_b64 s[66:67], -1
	s_cbranch_vccnz .LBB0_579
	v_cvt_pk_bf16_f32 v196, v202, v203
	v_cvt_pk_bf16_f32 v197, v200, v201
	global_store_dwordx2 v[136:137], v[196:197], off offset:1024
	v_cvt_pk_bf16_f32 v196, v206, v207
	v_cvt_pk_bf16_f32 v197, v204, v205
	s_mov_b64 s[66:67], 0
	global_store_dwordx2 v[136:137], v[196:197], off offset:1536

;     __device__ __forceinline__ void operator()(const f32x4 (&acc)[2][2][4][2], const Unit& u, int wr, int wc, int fr, int fq) const {
;     ...
;             for (int ai = 0; ai < 2; ++ai) {
;                 u32x2 g[16], t[16];
; #pragma unroll
;                 for (int k = 0; k < 16; ++k) { g[k] = tg[(ai * 16 + k) * 64]; if (mode != 1) t[k] = tm[(ai * 16 + k) * 64]; }
.LBB0_605:
	v_add_co_u32_e32 v174, vcc, 0x2000, v134
	s_nop 1
	v_addc_co_u32_e32 v175, vcc, 0, v135, vcc
	global_load_dwordx2 v[202:203], v[174:175], off
	s_and_b64 vcc, exec, s[8:9]
	s_cbranch_vccnz .LBB0_607
	v_add_co_u32_e32 v172, vcc, 0x2000, v136
	s_nop 1
	v_addc_co_u32_e32 v173, vcc, 0, v137, vcc
	global_load_dwordx2 v[172:173], v[172:173], off
.LBB0_607:
	v_add_co_u32_e32 v174, vcc, 0x2000, v134
	s_nop 1
	v_addc_co_u32_e32 v175, vcc, 0, v135, vcc
	global_load_dwordx2 v[204:205], v[174:175], off offset:512
	s_and_b64 vcc, exec, s[8:9]
	s_cbranch_vccnz .LBB0_609
	v_add_co_u32_e32 v170, vcc, 0x2000, v136
	s_nop 1
	v_addc_co_u32_e32 v171, vcc, 0, v137, vcc
	global_load_dwordx2 v[170:171], v[170:171], off offset:512
.LBB0_609:
	v_add_co_u32_e32 v174, vcc, 0x2000, v134
	s_nop 1
	v_addc_co_u32_e32 v175, vcc, 0, v135, vcc
	global_load_dwordx2 v[198:199], v[174:175], off offset:1024
	s_and_b64 vcc, exec, s[8:9]
	s_cbranch_vccnz .LBB0_611
	v_add_co_u32_e32 v168, vcc, 0x2000, v136
	s_nop 1
	v_addc_co_u32_e32 v169, vcc, 0, v137, vcc
	global_load_dwordx2 v[168:169], v[168:169], off offset:1024
.LBB0_611:
	v_add_co_u32_e32 v174, vcc, 0x2000, v134
	s_nop 1
	v_addc_co_u32_e32 v175, vcc, 0, v135, vcc
	global_load_dwordx2 v[200:201], v[174:175], off offset:1536
	s_and_b64 vcc, exec, s[8:9]
	s_cbranch_vccnz .LBB0_613
	v_add_co_u32_e32 v166, vcc, 0x2000, v136
	s_nop 1
	v_addc_co_u32_e32 v167, vcc, 0, v137, vcc
	global_load_dwordx2 v[166:167], v[166:167], off offset:1536
.LBB0_613:
	v_add_co_u32_e32 v174, vcc, 0x2000, v134
	s_nop 1
	v_addc_co_u32_e32 v175, vcc, 0, v135, vcc
	global_load_dwordx2 v[194:195], v[174:175], off offset:2048
	s_and_b64 vcc, exec, s[8:9]
	s_cbranch_vccnz .LBB0_615
	v_add_co_u32_e32 v164, vcc, 0x2000, v136
	s_nop 1
	v_addc_co_u32_e32 v165, vcc, 0, v137, vcc
	global_load_dwordx2 v[164:165], v[164:165], off offset:2048
.LBB0_615:
	v_add_co_u32_e32 v174, vcc, 0x2000, v134
	s_nop 1
	v_addc_co_u32_e32 v175, vcc, 0, v135, vcc
	global_load_dwordx2 v[196:197], v[174:175], off offset:2560
	s_and_b64 vcc, exec, s[8:9]
	s_cbranch_vccnz .LBB0_617
	v_add_co_u32_e32 v162, vcc, 0x2000, v136
	s_nop 1
	v_addc_co_u32_e32 v163, vcc, 0, v137, vcc
	global_load_dwordx2 v[162:163], v[162:163], off offset:2560
.LBB0_617:
	v_add_co_u32_e32 v174, vcc, 0x2000, v134
	s_nop 1
	v_addc_co_u32_e32 v175, vcc, 0, v135, vcc
	global_load_dwordx2 v[190:191], v[174:175], off offset:3072
	s_and_b64 vcc, exec, s[8:9]
	s_cbranch_vccnz .LBB0_619
	v_add_co_u32_e32 v160, vcc, 0x2000, v136
	s_nop 1
	v_addc_co_u32_e32 v161, vcc, 0, v137, vcc
	global_load_dwordx2 v[160:161], v[160:161], off offset:3072
.LBB0_619:
	v_add_co_u32_e32 v174, vcc, 0x2000, v134
	s_nop 1
	v_addc_co_u32_e32 v175, vcc, 0, v135, vcc
	global_load_dwordx2 v[192:193], v[174:175], off offset:3584
	s_and_b64 vcc, exec, s[8:9]
	s_cbranch_vccnz .LBB0_621
	v_add_co_u32_e32 v158, vcc, 0x2000, v136
	s_nop 1
	v_addc_co_u32_e32 v159, vcc, 0, v137, vcc
	global_load_dwordx2 v[158:159], v[158:159], off offset:3584
.LBB0_621:
	v_add_co_u32_e32 v174, vcc, 0x3000, v134
	s_nop 1
	v_addc_co_u32_e32 v175, vcc, 0, v135, vcc
	global_load_dwordx2 v[186:187], v[174:175], off
	s_and_b64 vcc, exec, s[8:9]
	s_cbranch_vccnz .LBB0_623
	v_add_co_u32_e32 v154, vcc, 0x3000, v136
	s_nop 1
	v_addc_co_u32_e32 v155, vcc, 0, v137, vcc
	global_load_dwordx2 v[154:155], v[154:155], off
.LBB0_623:
	v_add_co_u32_e32 v174, vcc, 0x3000, v134
	s_nop 1
	v_addc_co_u32_e32 v175, vcc, 0, v135, vcc
	global_load_dwordx2 v[188:189], v[174:175], off offset:512
	s_and_b64 vcc, exec, s[8:9]
	s_cbranch_vccnz .LBB0_625
	v_add_co_u32_e32 v156, vcc, 0x3000, v136
	s_nop 1
	v_addc_co_u32_e32 v157, vcc, 0, v137, vcc
	global_load_dwordx2 v[156:157], v[156:157], off offset:512
.LBB0_625:
	v_add_co_u32_e32 v174, vcc, 0x3000, v134
	s_nop 1
	v_addc_co_u32_e32 v175, vcc, 0, v135, vcc
	global_load_dwordx2 v[182:183], v[174:175], off offset:1024
	s_and_b64 vcc, exec, s[8:9]
	s_cbranch_vccnz .LBB0_627
	v_add_co_u32_e32 v150, vcc, 0x3000, v136
	s_nop 1
	v_addc_co_u32_e32 v151, vcc, 0, v137, vcc
	global_load_dwordx2 v[150:151], v[150:151], off offset:1024
.LBB0_627:
	v_add_co_u32_e32 v174, vcc, 0x3000, v134
	s_nop 1
	v_addc_co_u32_e32 v175, vcc, 0, v135, vcc
	global_load_dwordx2 v[184:185], v[174:175], off offset:1536
	s_and_b64 vcc, exec, s[8:9]
	s_cbranch_vccnz .LBB0_629
	v_add_co_u32_e32 v152, vcc, 0x3000, v136
	s_nop 1
	v_addc_co_u32_e32 v153, vcc, 0, v137, vcc
	global_load_dwordx2 v[152:153], v[152:153], off offset:1536
.LBB0_629:
	v_add_co_u32_e32 v174, vcc, 0x3000, v134
	s_nop 1
	v_addc_co_u32_e32 v175, vcc, 0, v135, vcc
	global_load_dwordx2 v[178:179], v[174:175], off offset:2048
	s_and_b64 vcc, exec, s[8:9]
	s_cbranch_vccnz .LBB0_631
	v_add_co_u32_e32 v146, vcc, 0x3000, v136
	s_nop 1
	v_addc_co_u32_e32 v147, vcc, 0, v137, vcc
	global_load_dwordx2 v[146:147], v[146:147], off offset:2048
.LBB0_631:
	v_add_co_u32_e32 v174, vcc, 0x3000, v134
	s_nop 1
	v_addc_co_u32_e32 v175, vcc, 0, v135, vcc
	global_load_dwordx2 v[180:181], v[174:175], off offset:2560
	s_and_b64 vcc, exec, s[8:9]
	s_cbranch_vccnz .LBB0_633
	v_add_co_u32_e32 v148, vcc, 0x3000, v136
	s_nop 1
	v_addc_co_u32_e32 v149, vcc, 0, v137, vcc
	global_load_dwordx2 v[148:149], v[148:149], off offset:2560
.LBB0_633:
	v_add_co_u32_e32 v174, vcc, 0x3000, v134
	s_nop 1
	v_addc_co_u32_e32 v175, vcc, 0, v135, vcc
	global_load_dwordx2 v[174:175], v[174:175], off offset:3072
	s_and_b64 vcc, exec, s[8:9]
	s_cbranch_vccnz .LBB0_635
	v_add_co_u32_e32 v138, vcc, 0x3000, v136
	s_nop 1
	v_addc_co_u32_e32 v139, vcc, 0, v137, vcc
	global_load_dwordx2 v[138:139], v[138:139], off offset:3072
.LBB0_635:
	v_add_co_u32_e32 v176, vcc, 0x3000, v134
	s_nop 1
	v_addc_co_u32_e32 v177, vcc, 0, v135, vcc
	global_load_dwordx2 v[176:177], v[176:177], off offset:3584
	s_and_b64 vcc, exec, s[8:9]
	s_cbranch_vccnz .LBB0_637
	v_add_co_u32_e32 v140, vcc, 0x3000, v136
	s_nop 1
	v_addc_co_u32_e32 v141, vcc, 0, v137, vcc
	global_load_dwordx2 v[140:141], v[140:141], off offset:3584

; __device__ __forceinline__ u32x2 pk4(f32x4 v) { u32x2 w; w.x = pk2(v[0], v[1]); w.y = pk2(v[2], v[3]); return w; }
;     __device__ __forceinline__ void operator()(const f32x4 (&acc)[2][2][4][2], const Unit& u, int wr, int wc, int fr, int fq) const {
;     ...
;         if (mode == 0) {
; #pragma unroll
;             for (int ai = 0; ai < 2; ++ai)
; #pragma unroll
;                 for (int bj = 0; bj < 2; ++bj)
; #pragma unroll
;                     for (int m = 0; m < 4; ++m)
; #pragma unroll
;                         for (int n = 0; n < 2; ++n) { const int idx = ((ai * 2 + bj) * 4 + m) * 2 + n; f32x4 a = acc[ai][bj][m][n], sg;
; #pragma unroll
;                             for (int e = 0; e < 4; ++e) sg[e] = __builtin_amdgcn_rcpf(1.0f + __builtin_amdgcn_exp2f((-1.4426950408889634f / 32.0f) * a[e]));
;                             tg[idx * 64] = pk4(sg); if (n) asm volatile("" ::: "memory"); }
.LBB0_670:
	v_mul_f32_e32 v124, 0xbd38aa3b, v124
	v_mul_f32_e32 v125, 0xbd38aa3b, v125
	v_exp_f32_e32 v124, v124
	v_exp_f32_e32 v125, v125
	v_mul_f32_e32 v120, 0xbd38aa3b, v120
	v_exp_f32_e32 v128, v120
	v_mul_f32_e32 v120, 0xbd38aa3b, v121
	v_add_f32_e32 v124, 1.0, v124
	v_add_f32_e32 v125, 1.0, v125
	v_mul_f32_e32 v126, 0xbd38aa3b, v126
	v_mul_f32_e32 v127, 0xbd38aa3b, v127
	v_exp_f32_e32 v121, v120
	v_mul_f32_e32 v122, 0xbd38aa3b, v122
	v_rcp_f32_e32 v124, v124
	v_exp_f32_e32 v126, v126
	v_exp_f32_e32 v127, v127
	v_rcp_f32_e32 v125, v125
	v_exp_f32_e32 v122, v122
	v_mul_f32_e32 v123, 0xbd38aa3b, v123
	v_exp_f32_e32 v123, v123
	v_add_f32_e32 v121, 1.0, v121
	v_add_f32_e32 v126, 1.0, v126
	v_add_f32_e32 v127, 1.0, v127
	v_cvt_pk_bf16_f32 v120, v124, v125
	v_rcp_f32_e32 v125, v121
	v_add_f32_e32 v121, 1.0, v122
	v_rcp_f32_e32 v126, v126
	v_rcp_f32_e32 v127, v127
	v_add_f32_e32 v124, 1.0, v128
	v_rcp_f32_e32 v122, v121
	v_add_f32_e32 v121, 1.0, v123
	v_rcp_f32_e32 v124, v124
	v_rcp_f32_e32 v123, v121
	v_mul_f32_e32 v116, 0xbd38aa3b, v116
	v_mul_f32_e32 v117, 0xbd38aa3b, v117
	v_exp_f32_e32 v116, v116
	v_exp_f32_e32 v117, v117
	v_cvt_pk_bf16_f32 v121, v126, v127
	global_store_dwordx2 v[134:135], v[120:121], off
	v_cvt_pk_bf16_f32 v120, v124, v125
	v_cvt_pk_bf16_f32 v121, v122, v123
	v_mul_f32_e32 v112, 0xbd38aa3b, v112
	global_store_dwordx2 v[134:135], v[120:121], off offset:512
	v_exp_f32_e32 v120, v112
	v_mul_f32_e32 v112, 0xbd38aa3b, v113
	v_add_f32_e32 v116, 1.0, v116
	v_add_f32_e32 v117, 1.0, v117
	v_mul_f32_e32 v118, 0xbd38aa3b, v118
	v_mul_f32_e32 v119, 0xbd38aa3b, v119
	v_exp_f32_e32 v113, v112
	v_mul_f32_e32 v114, 0xbd38aa3b, v114
	v_rcp_f32_e32 v116, v116
	v_exp_f32_e32 v118, v118
	v_exp_f32_e32 v119, v119
	v_rcp_f32_e32 v117, v117
	v_exp_f32_e32 v114, v114
	v_mul_f32_e32 v115, 0xbd38aa3b, v115
	v_exp_f32_e32 v115, v115
	v_add_f32_e32 v113, 1.0, v113
	v_add_f32_e32 v118, 1.0, v118
	v_add_f32_e32 v119, 1.0, v119
	v_cvt_pk_bf16_f32 v112, v116, v117
	v_rcp_f32_e32 v117, v113
	v_add_f32_e32 v113, 1.0, v114
	v_rcp_f32_e32 v118, v118
	v_rcp_f32_e32 v119, v119
	v_add_f32_e32 v116, 1.0, v120
	v_rcp_f32_e32 v114, v113
	v_add_f32_e32 v113, 1.0, v115
	v_rcp_f32_e32 v116, v116
	v_rcp_f32_e32 v115, v113
	v_mul_f32_e32 v108, 0xbd38aa3b, v108
	v_mul_f32_e32 v109, 0xbd38aa3b, v109
	v_exp_f32_e32 v108, v108
	v_exp_f32_e32 v109, v109
	v_cvt_pk_bf16_f32 v113, v118, v119
	global_store_dwordx2 v[134:135], v[112:113], off offset:1024
	v_cvt_pk_bf16_f32 v112, v116, v117
	v_cvt_pk_bf16_f32 v113, v114, v115
	v_mul_f32_e32 v104, 0xbd38aa3b, v104
	global_store_dwordx2 v[134:135], v[112:113], off offset:1536
	v_exp_f32_e32 v112, v104
	v_mul_f32_e32 v104, 0xbd38aa3b, v105
	v_add_f32_e32 v108, 1.0, v108
	v_add_f32_e32 v109, 1.0, v109
	v_mul_f32_e32 v110, 0xbd38aa3b, v110
	v_mul_f32_e32 v111, 0xbd38aa3b, v111
	v_exp_f32_e32 v105, v104
	v_mul_f32_e32 v106, 0xbd38aa3b, v106
	v_rcp_f32_e32 v108, v108
	v_exp_f32_e32 v110, v110
	v_exp_f32_e32 v111, v111
	v_rcp_f32_e32 v109, v109
	v_exp_f32_e32 v106, v106
	v_mul_f32_e32 v107, 0xbd38aa3b, v107
	v_exp_f32_e32 v107, v107
	v_add_f32_e32 v105, 1.0, v105
	v_add_f32_e32 v110, 1.0, v110
	v_add_f32_e32 v111, 1.0, v111
	v_cvt_pk_bf16_f32 v104, v108, v109
	v_rcp_f32_e32 v109, v105
	v_add_f32_e32 v105, 1.0, v106
	v_rcp_f32_e32 v110, v110
	v_rcp_f32_e32 v111, v111
	v_add_f32_e32 v108, 1.0, v112
	v_rcp_f32_e32 v106, v105
	v_add_f32_e32 v105, 1.0, v107
	v_rcp_f32_e32 v108, v108
	v_rcp_f32_e32 v107, v105
	v_mul_f32_e32 v100, 0xbd38aa3b, v100
	v_mul_f32_e32 v101, 0xbd38aa3b, v101
	v_mul_f32_e32 v92, 0xbd38aa3b, v92
	v_mul_f32_e32 v93, 0xbd38aa3b, v93
	v_mul_f32_e32 v94, 0xbd38aa3b, v94
	v_mul_f32_e32 v95, 0xbd38aa3b, v95
	v_exp_f32_e32 v100, v100
	v_exp_f32_e32 v101, v101
	v_exp_f32_e32 v92, v92
	v_exp_f32_e32 v93, v93
	v_exp_f32_e32 v94, v94
	v_exp_f32_e32 v95, v95
	v_cvt_pk_bf16_f32 v105, v110, v111
	global_store_dwordx2 v[134:135], v[104:105], off offset:2048
	v_cvt_pk_bf16_f32 v104, v108, v109
	v_cvt_pk_bf16_f32 v105, v106, v107
	v_mul_f32_e32 v96, 0xbd38aa3b, v96
	global_store_dwordx2 v[134:135], v[104:105], off offset:2560
	v_exp_f32_e32 v104, v96
	v_mul_f32_e32 v96, 0xbd38aa3b, v97
	v_mul_f32_e32 v88, 0xbd38aa3b, v88
	v_add_f32_e32 v100, 1.0, v100
	v_add_f32_e32 v101, 1.0, v101
	v_mul_f32_e32 v102, 0xbd38aa3b, v102
	v_mul_f32_e32 v103, 0xbd38aa3b, v103
	v_exp_f32_e32 v97, v96
	v_mul_f32_e32 v98, 0xbd38aa3b, v98
	v_add_f32_e32 v92, 1.0, v92
	v_add_f32_e32 v93, 1.0, v93
	v_add_f32_e32 v94, 1.0, v94
	v_add_f32_e32 v95, 1.0, v95
	v_exp_f32_e32 v88, v88
	v_mul_f32_e32 v89, 0xbd38aa3b, v89
	v_rcp_f32_e32 v100, v100
	v_exp_f32_e32 v102, v102
	v_exp_f32_e32 v103, v103
	v_rcp_f32_e32 v101, v101
	v_exp_f32_e32 v98, v98
	v_mul_f32_e32 v99, 0xbd38aa3b, v99
	v_rcp_f32_e32 v92, v92
	v_rcp_f32_e32 v93, v93
	v_rcp_f32_e32 v94, v94
	v_rcp_f32_e32 v95, v95
	v_exp_f32_e32 v89, v89
	v_exp_f32_e32 v99, v99
	v_add_f32_e32 v97, 1.0, v97
	v_add_f32_e32 v88, 1.0, v88
	v_add_f32_e32 v102, 1.0, v102
	v_add_f32_e32 v103, 1.0, v103
	v_cvt_pk_bf16_f32 v96, v100, v101
	v_rcp_f32_e32 v101, v97
	v_add_f32_e32 v97, 1.0, v98
	v_cvt_pk_bf16_f32 v92, v92, v93
	v_cvt_pk_bf16_f32 v93, v94, v95
	v_rcp_f32_e32 v94, v88
	v_add_f32_e32 v88, 1.0, v89
	v_mul_f32_e32 v89, 0xbd38aa3b, v90
	v_rcp_f32_e32 v102, v102
	v_rcp_f32_e32 v103, v103
	v_add_f32_e32 v100, 1.0, v104
	v_rcp_f32_e32 v98, v97
	v_add_f32_e32 v97, 1.0, v99
	v_exp_f32_e32 v89, v89
	v_mul_f32_e32 v90, 0xbd38aa3b, v91
	v_rcp_f32_e32 v100, v100
	v_rcp_f32_e32 v99, v97
	v_exp_f32_e32 v90, v90
	v_cvt_pk_bf16_f32 v97, v102, v103
	v_rcp_f32_e32 v91, v88
	v_add_f32_e32 v88, 1.0, v89
; __device__ __forceinline__ u32x2 pk4(f32x4 v) { u32x2 w; w.x = pk2(v[0], v[1]); w.y = pk2(v[2], v[3]); return w; }
;     __device__ __forceinline__ void operator()(const f32x4 (&acc)[2][2][4][2], const Unit& u, int wr, int wc, int fr, int fq) const {
;     ...
;         if (mode == 0) {
; #pragma unroll
;             for (int ai = 0; ai < 2; ++ai)
; #pragma unroll
;                 for (int bj = 0; bj < 2; ++bj)
; #pragma unroll
;                     for (int m = 0; m < 4; ++m)
; #pragma unroll
;                         for (int n = 0; n < 2; ++n) { const int idx = ((ai * 2 + bj) * 4 + m) * 2 + n; f32x4 a = acc[ai][bj][m][n], sg;
; #pragma unroll
;                             for (int e = 0; e < 4; ++e) sg[e] = __builtin_amdgcn_rcpf(1.0f + __builtin_amdgcn_exp2f((-1.4426950408889634f / 32.0f) * a[e]));
;                             tg[idx * 64] = pk4(sg); if (n) asm volatile("" ::: "memory"); }
	global_store_dwordx2 v[134:135], v[96:97], off offset:3072
	v_cvt_pk_bf16_f32 v96, v100, v101
	v_cvt_pk_bf16_f32 v97, v98, v99
	v_rcp_f32_e32 v95, v88
	v_add_f32_e32 v88, 1.0, v90
	global_store_dwordx2 v[134:135], v[96:97], off offset:3584
	v_rcp_f32_e32 v96, v88
	v_mul_f32_e32 v84, 0xbd38aa3b, v84
	v_mul_f32_e32 v85, 0xbd38aa3b, v85
	s_movk_i32 s8, 0x1000
	v_exp_f32_e32 v84, v84
	v_exp_f32_e32 v85, v85
	v_add_co_u32_e32 v88, vcc, s8, v134
	v_cvt_pk_bf16_f32 v90, v94, v91
	s_nop 0
	v_addc_co_u32_e32 v89, vcc, 0, v135, vcc
	v_cvt_pk_bf16_f32 v91, v95, v96
	v_mul_f32_e32 v80, 0xbd38aa3b, v80
	global_store_dwordx2 v[88:89], v[90:91], off offset:512
	v_exp_f32_e32 v90, v80
	v_mul_f32_e32 v80, 0xbd38aa3b, v81
	v_add_f32_e32 v84, 1.0, v84
	v_add_f32_e32 v85, 1.0, v85
	v_mul_f32_e32 v86, 0xbd38aa3b, v86
	v_mul_f32_e32 v87, 0xbd38aa3b, v87
	v_exp_f32_e32 v81, v80
	v_mul_f32_e32 v82, 0xbd38aa3b, v82
	v_rcp_f32_e32 v84, v84
	v_exp_f32_e32 v86, v86
	v_exp_f32_e32 v87, v87
	v_rcp_f32_e32 v85, v85
	v_exp_f32_e32 v82, v82
	v_mul_f32_e32 v83, 0xbd38aa3b, v83
	v_exp_f32_e32 v83, v83
	v_add_f32_e32 v81, 1.0, v81
	v_add_f32_e32 v86, 1.0, v86
	v_add_f32_e32 v87, 1.0, v87
	v_cvt_pk_bf16_f32 v80, v84, v85
	v_rcp_f32_e32 v85, v81
	v_add_f32_e32 v81, 1.0, v82
	v_rcp_f32_e32 v86, v86
	v_rcp_f32_e32 v87, v87
	v_add_f32_e32 v84, 1.0, v90
	v_rcp_f32_e32 v82, v81
	v_add_f32_e32 v81, 1.0, v83
	v_rcp_f32_e32 v84, v84
	v_rcp_f32_e32 v83, v81
	v_mul_f32_e32 v76, 0xbd38aa3b, v76
	v_mul_f32_e32 v77, 0xbd38aa3b, v77
	v_exp_f32_e32 v76, v76
	v_exp_f32_e32 v77, v77
	global_store_dwordx2 v[88:89], v[92:93], off
	v_cvt_pk_bf16_f32 v81, v86, v87
	global_store_dwordx2 v[88:89], v[80:81], off offset:1024
	v_cvt_pk_bf16_f32 v80, v84, v85
	v_cvt_pk_bf16_f32 v81, v82, v83
	v_mul_f32_e32 v72, 0xbd38aa3b, v72
	global_store_dwordx2 v[88:89], v[80:81], off offset:1536
	v_exp_f32_e32 v80, v72
	v_mul_f32_e32 v72, 0xbd38aa3b, v73
	v_add_f32_e32 v76, 1.0, v76
	v_add_f32_e32 v77, 1.0, v77
	v_mul_f32_e32 v78, 0xbd38aa3b, v78
	v_mul_f32_e32 v79, 0xbd38aa3b, v79
	v_exp_f32_e32 v73, v72
	v_mul_f32_e32 v74, 0xbd38aa3b, v74
	v_rcp_f32_e32 v76, v76
	v_exp_f32_e32 v78, v78
	v_exp_f32_e32 v79, v79
	v_rcp_f32_e32 v77, v77
	v_exp_f32_e32 v74, v74
	v_mul_f32_e32 v75, 0xbd38aa3b, v75
	v_exp_f32_e32 v75, v75
	v_add_f32_e32 v73, 1.0, v73
	v_add_f32_e32 v78, 1.0, v78
	v_add_f32_e32 v79, 1.0, v79
	v_cvt_pk_bf16_f32 v72, v76, v77
	v_rcp_f32_e32 v77, v73
	v_add_f32_e32 v73, 1.0, v74
	v_rcp_f32_e32 v78, v78
	v_rcp_f32_e32 v79, v79
	v_add_f32_e32 v76, 1.0, v80
	v_rcp_f32_e32 v74, v73
	v_add_f32_e32 v73, 1.0, v75
	v_rcp_f32_e32 v76, v76
	v_rcp_f32_e32 v75, v73
	v_mul_f32_e32 v68, 0xbd38aa3b, v68
	v_mul_f32_e32 v69, 0xbd38aa3b, v69
	v_mul_f32_e32 v60, 0xbd38aa3b, v60
	v_mul_f32_e32 v61, 0xbd38aa3b, v61
	v_mul_f32_e32 v62, 0xbd38aa3b, v62
	v_mul_f32_e32 v63, 0xbd38aa3b, v63
	v_exp_f32_e32 v68, v68
	v_exp_f32_e32 v69, v69
	v_exp_f32_e32 v60, v60
	v_exp_f32_e32 v61, v61
	v_exp_f32_e32 v62, v62
	v_exp_f32_e32 v63, v63
	v_cvt_pk_bf16_f32 v73, v78, v79
	global_store_dwordx2 v[88:89], v[72:73], off offset:2048
	v_cvt_pk_bf16_f32 v72, v76, v77
	v_cvt_pk_bf16_f32 v73, v74, v75
	v_mul_f32_e32 v64, 0xbd38aa3b, v64
	global_store_dwordx2 v[88:89], v[72:73], off offset:2560
	v_exp_f32_e32 v72, v64
	v_mul_f32_e32 v64, 0xbd38aa3b, v65
	v_mul_f32_e32 v56, 0xbd38aa3b, v56
	v_add_f32_e32 v68, 1.0, v68
	v_add_f32_e32 v69, 1.0, v69
	v_mul_f32_e32 v70, 0xbd38aa3b, v70
	v_mul_f32_e32 v71, 0xbd38aa3b, v71
	v_exp_f32_e32 v65, v64
	v_mul_f32_e32 v66, 0xbd38aa3b, v66
	v_add_f32_e32 v60, 1.0, v60
	v_add_f32_e32 v61, 1.0, v61
	v_add_f32_e32 v62, 1.0, v62
	v_add_f32_e32 v63, 1.0, v63
	v_exp_f32_e32 v56, v56
	v_mul_f32_e32 v57, 0xbd38aa3b, v57
	v_rcp_f32_e32 v68, v68
	v_exp_f32_e32 v70, v70
	v_exp_f32_e32 v71, v71
	v_rcp_f32_e32 v69, v69
	v_exp_f32_e32 v66, v66
	v_mul_f32_e32 v67, 0xbd38aa3b, v67
	v_rcp_f32_e32 v60, v60
	v_rcp_f32_e32 v61, v61
	v_rcp_f32_e32 v62, v62
	v_rcp_f32_e32 v63, v63
	v_exp_f32_e32 v57, v57
	v_exp_f32_e32 v67, v67
	v_add_f32_e32 v65, 1.0, v65
	v_add_f32_e32 v56, 1.0, v56
	v_add_f32_e32 v70, 1.0, v70
	v_add_f32_e32 v71, 1.0, v71
	v_cvt_pk_bf16_f32 v64, v68, v69
	v_rcp_f32_e32 v69, v65
	v_add_f32_e32 v65, 1.0, v66
	v_cvt_pk_bf16_f32 v60, v60, v61
	v_cvt_pk_bf16_f32 v61, v62, v63
	v_rcp_f32_e32 v62, v56
	v_add_f32_e32 v56, 1.0, v57
	v_mul_f32_e32 v57, 0xbd38aa3b, v58
	v_rcp_f32_e32 v70, v70
	v_rcp_f32_e32 v71, v71
	v_add_f32_e32 v68, 1.0, v72
	v_rcp_f32_e32 v66, v65
	v_add_f32_e32 v65, 1.0, v67
	v_exp_f32_e32 v57, v57
	v_mul_f32_e32 v58, 0xbd38aa3b, v59
	v_rcp_f32_e32 v68, v68
	v_rcp_f32_e32 v67, v65
	v_exp_f32_e32 v58, v58
	v_cvt_pk_bf16_f32 v65, v70, v71
	v_rcp_f32_e32 v59, v56
	v_add_f32_e32 v56, 1.0, v57
	global_store_dwordx2 v[88:89], v[64:65], off offset:3072
	v_cvt_pk_bf16_f32 v64, v68, v69
	v_cvt_pk_bf16_f32 v65, v66, v67
	v_rcp_f32_e32 v63, v56
	v_add_f32_e32 v56, 1.0, v58
	global_store_dwordx2 v[88:89], v[64:65], off offset:3584
	v_rcp_f32_e32 v64, v56
	v_mul_f32_e32 v52, 0xbd38aa3b, v52
	v_mul_f32_e32 v53, 0xbd38aa3b, v53
	s_movk_i32 s8, 0x2000
	v_exp_f32_e32 v52, v52
	v_exp_f32_e32 v53, v53
	v_add_co_u32_e32 v56, vcc, s8, v134
	v_cvt_pk_bf16_f32 v58, v62, v59
	s_nop 0
	v_addc_co_u32_e32 v57, vcc, 0, v135, vcc
	v_cvt_pk_bf16_f32 v59, v63, v64
	v_mul_f32_e32 v48, 0xbd38aa3b, v48
	global_store_dwordx2 v[56:57], v[58:59], off offset:512
	v_exp_f32_e32 v58, v48
	v_mul_f32_e32 v48, 0xbd38aa3b, v49
	v_add_f32_e32 v52, 1.0, v52
	v_add_f32_e32 v53, 1.0, v53
	v_mul_f32_e32 v54, 0xbd38aa3b, v54
	v_mul_f32_e32 v55, 0xbd38aa3b, v55
	v_exp_f32_e32 v49, v48
	v_mul_f32_e32 v50, 0xbd38aa3b, v50
	v_rcp_f32_e32 v52, v52
; __device__ __forceinline__ u32x2 pk4(f32x4 v) { u32x2 w; w.x = pk2(v[0], v[1]); w.y = pk2(v[2], v[3]); return w; }
;     __device__ __forceinline__ void operator()(const f32x4 (&acc)[2][2][4][2], const Unit& u, int wr, int wc, int fr, int fq) const {
;     ...
;         if (mode == 0) {
; #pragma unroll
;             for (int ai = 0; ai < 2; ++ai)
; #pragma unroll
;                 for (int bj = 0; bj < 2; ++bj)
; #pragma unroll
;                     for (int m = 0; m < 4; ++m)
; #pragma unroll
;                         for (int n = 0; n < 2; ++n) { const int idx = ((ai * 2 + bj) * 4 + m) * 2 + n; f32x4 a = acc[ai][bj][m][n], sg;
; #pragma unroll
;                             for (int e = 0; e < 4; ++e) sg[e] = __builtin_amdgcn_rcpf(1.0f + __builtin_amdgcn_exp2f((-1.4426950408889634f / 32.0f) * a[e]));
;                             tg[idx * 64] = pk4(sg); if (n) asm volatile("" ::: "memory"); }
	v_exp_f32_e32 v54, v54
	v_exp_f32_e32 v55, v55
	v_rcp_f32_e32 v53, v53
	v_exp_f32_e32 v50, v50
	v_mul_f32_e32 v51, 0xbd38aa3b, v51
	v_exp_f32_e32 v51, v51
	v_add_f32_e32 v49, 1.0, v49
	v_add_f32_e32 v54, 1.0, v54
	v_add_f32_e32 v55, 1.0, v55
	v_cvt_pk_bf16_f32 v48, v52, v53
	v_rcp_f32_e32 v53, v49
	v_add_f32_e32 v49, 1.0, v50
	v_rcp_f32_e32 v54, v54
	v_rcp_f32_e32 v55, v55
	v_add_f32_e32 v52, 1.0, v58
	v_rcp_f32_e32 v50, v49
	v_add_f32_e32 v49, 1.0, v51
	v_rcp_f32_e32 v52, v52
	v_rcp_f32_e32 v51, v49
	v_mul_f32_e32 v44, 0xbd38aa3b, v44
	v_mul_f32_e32 v45, 0xbd38aa3b, v45
	v_exp_f32_e32 v44, v44
	v_exp_f32_e32 v45, v45
	global_store_dwordx2 v[56:57], v[60:61], off
	v_cvt_pk_bf16_f32 v49, v54, v55
	global_store_dwordx2 v[56:57], v[48:49], off offset:1024
	v_cvt_pk_bf16_f32 v48, v52, v53
	v_cvt_pk_bf16_f32 v49, v50, v51
	v_mul_f32_e32 v40, 0xbd38aa3b, v40
	global_store_dwordx2 v[56:57], v[48:49], off offset:1536
	v_exp_f32_e32 v48, v40
	v_mul_f32_e32 v40, 0xbd38aa3b, v41
	v_add_f32_e32 v44, 1.0, v44
	v_add_f32_e32 v45, 1.0, v45
	v_mul_f32_e32 v46, 0xbd38aa3b, v46
	v_mul_f32_e32 v47, 0xbd38aa3b, v47
	v_exp_f32_e32 v41, v40
	v_mul_f32_e32 v42, 0xbd38aa3b, v42
	v_rcp_f32_e32 v44, v44
	v_exp_f32_e32 v46, v46
	v_exp_f32_e32 v47, v47
	v_rcp_f32_e32 v45, v45
	v_exp_f32_e32 v42, v42
	v_mul_f32_e32 v43, 0xbd38aa3b, v43
	v_exp_f32_e32 v43, v43
	v_add_f32_e32 v41, 1.0, v41
	v_add_f32_e32 v46, 1.0, v46
	v_add_f32_e32 v47, 1.0, v47
	v_cvt_pk_bf16_f32 v40, v44, v45
	v_rcp_f32_e32 v45, v41
	v_add_f32_e32 v41, 1.0, v42
	v_rcp_f32_e32 v46, v46
	v_rcp_f32_e32 v47, v47
	v_add_f32_e32 v44, 1.0, v48
	v_rcp_f32_e32 v42, v41
	v_add_f32_e32 v41, 1.0, v43
	v_rcp_f32_e32 v44, v44
	v_rcp_f32_e32 v43, v41
	v_mul_f32_e32 v36, 0xbd38aa3b, v36
	v_mul_f32_e32 v37, 0xbd38aa3b, v37
	v_mul_f32_e32 v28, 0xbd38aa3b, v28
	v_mul_f32_e32 v29, 0xbd38aa3b, v29
	v_mul_f32_e32 v30, 0xbd38aa3b, v30
	v_mul_f32_e32 v31, 0xbd38aa3b, v31
	v_exp_f32_e32 v36, v36
	v_exp_f32_e32 v37, v37
	v_exp_f32_e32 v28, v28
	v_exp_f32_e32 v29, v29
	v_exp_f32_e32 v30, v30
	v_exp_f32_e32 v31, v31
	v_cvt_pk_bf16_f32 v41, v46, v47
	global_store_dwordx2 v[56:57], v[40:41], off offset:2048
	v_cvt_pk_bf16_f32 v40, v44, v45
	v_cvt_pk_bf16_f32 v41, v42, v43
	v_mul_f32_e32 v32, 0xbd38aa3b, v32
	global_store_dwordx2 v[56:57], v[40:41], off offset:2560
	v_exp_f32_e32 v40, v32
	v_mul_f32_e32 v32, 0xbd38aa3b, v33
	v_mul_f32_e32 v24, 0xbd38aa3b, v24
	v_add_f32_e32 v36, 1.0, v36
	v_add_f32_e32 v37, 1.0, v37
	v_mul_f32_e32 v38, 0xbd38aa3b, v38
	v_mul_f32_e32 v39, 0xbd38aa3b, v39
	v_exp_f32_e32 v33, v32
	v_mul_f32_e32 v34, 0xbd38aa3b, v34
	v_add_f32_e32 v28, 1.0, v28
	v_add_f32_e32 v29, 1.0, v29
	v_add_f32_e32 v30, 1.0, v30
	v_add_f32_e32 v31, 1.0, v31
	v_exp_f32_e32 v24, v24
	v_mul_f32_e32 v25, 0xbd38aa3b, v25
	v_rcp_f32_e32 v36, v36
	v_exp_f32_e32 v38, v38
	v_exp_f32_e32 v39, v39
	v_rcp_f32_e32 v37, v37
	v_exp_f32_e32 v34, v34
	v_mul_f32_e32 v35, 0xbd38aa3b, v35
	v_rcp_f32_e32 v28, v28
	v_rcp_f32_e32 v29, v29
	v_rcp_f32_e32 v30, v30
	v_rcp_f32_e32 v31, v31
	v_exp_f32_e32 v25, v25
	v_exp_f32_e32 v35, v35
	v_add_f32_e32 v33, 1.0, v33
	v_add_f32_e32 v24, 1.0, v24
	v_add_f32_e32 v38, 1.0, v38
	v_add_f32_e32 v39, 1.0, v39
	v_cvt_pk_bf16_f32 v32, v36, v37
	v_rcp_f32_e32 v37, v33
	v_add_f32_e32 v33, 1.0, v34
	v_cvt_pk_bf16_f32 v28, v28, v29
	v_cvt_pk_bf16_f32 v29, v30, v31
	v_rcp_f32_e32 v30, v24
	v_add_f32_e32 v24, 1.0, v25
	v_mul_f32_e32 v25, 0xbd38aa3b, v26
	v_rcp_f32_e32 v38, v38
	v_rcp_f32_e32 v39, v39
	v_add_f32_e32 v36, 1.0, v40
	v_rcp_f32_e32 v34, v33
	v_add_f32_e32 v33, 1.0, v35
	v_exp_f32_e32 v25, v25
	v_mul_f32_e32 v26, 0xbd38aa3b, v27
	v_rcp_f32_e32 v36, v36
	v_rcp_f32_e32 v35, v33
	v_exp_f32_e32 v26, v26
	v_cvt_pk_bf16_f32 v33, v38, v39
	v_rcp_f32_e32 v27, v24
	v_add_f32_e32 v24, 1.0, v25
	global_store_dwordx2 v[56:57], v[32:33], off offset:3072
; __device__ __forceinline__ u32x2 pk4(f32x4 v) { u32x2 w; w.x = pk2(v[0], v[1]); w.y = pk2(v[2], v[3]); return w; }
;     __device__ __forceinline__ void operator()(const f32x4 (&acc)[2][2][4][2], const Unit& u, int wr, int wc, int fr, int fq) const {
;     ...
;         if (mode == 0) {
; #pragma unroll
;             for (int ai = 0; ai < 2; ++ai)
; #pragma unroll
;                 for (int bj = 0; bj < 2; ++bj)
; #pragma unroll
;                     for (int m = 0; m < 4; ++m)
; #pragma unroll
;                         for (int n = 0; n < 2; ++n) { const int idx = ((ai * 2 + bj) * 4 + m) * 2 + n; f32x4 a = acc[ai][bj][m][n], sg;
; #pragma unroll
;                             for (int e = 0; e < 4; ++e) sg[e] = __builtin_amdgcn_rcpf(1.0f + __builtin_amdgcn_exp2f((-1.4426950408889634f / 32.0f) * a[e]));
;                             tg[idx * 64] = pk4(sg); if (n) asm volatile("" ::: "memory"); }
	v_cvt_pk_bf16_f32 v32, v36, v37
	v_cvt_pk_bf16_f32 v33, v34, v35
	v_rcp_f32_e32 v31, v24
	v_add_f32_e32 v24, 1.0, v26
	global_store_dwordx2 v[56:57], v[32:33], off offset:3584
	v_rcp_f32_e32 v32, v24
	v_mul_f32_e32 v20, 0xbd38aa3b, v20
	v_mul_f32_e32 v21, 0xbd38aa3b, v21
	s_movk_i32 s8, 0x3000
	v_exp_f32_e32 v20, v20
	v_exp_f32_e32 v21, v21
	v_add_co_u32_e32 v24, vcc, s8, v134
	v_cvt_pk_bf16_f32 v26, v30, v27
	s_nop 0
	v_addc_co_u32_e32 v25, vcc, 0, v135, vcc
	v_cvt_pk_bf16_f32 v27, v31, v32
	v_mul_f32_e32 v16, 0xbd38aa3b, v16
	global_store_dwordx2 v[24:25], v[26:27], off offset:512
	v_exp_f32_e32 v26, v16
	v_mul_f32_e32 v16, 0xbd38aa3b, v17
	v_add_f32_e32 v20, 1.0, v20
	v_add_f32_e32 v21, 1.0, v21
	v_mul_f32_e32 v22, 0xbd38aa3b, v22
	v_mul_f32_e32 v23, 0xbd38aa3b, v23
	v_exp_f32_e32 v17, v16
	v_mul_f32_e32 v18, 0xbd38aa3b, v18
	v_rcp_f32_e32 v20, v20
	v_exp_f32_e32 v22, v22
	v_exp_f32_e32 v23, v23
	v_rcp_f32_e32 v21, v21
	v_exp_f32_e32 v18, v18
	v_mul_f32_e32 v19, 0xbd38aa3b, v19
	v_exp_f32_e32 v19, v19
	v_add_f32_e32 v17, 1.0, v17
	v_add_f32_e32 v22, 1.0, v22
	v_add_f32_e32 v23, 1.0, v23
	v_cvt_pk_bf16_f32 v16, v20, v21
	v_rcp_f32_e32 v21, v17
	v_add_f32_e32 v17, 1.0, v18
	v_rcp_f32_e32 v22, v22
	v_rcp_f32_e32 v23, v23
	v_add_f32_e32 v20, 1.0, v26
	v_rcp_f32_e32 v18, v17
	v_add_f32_e32 v17, 1.0, v19
	v_rcp_f32_e32 v20, v20
	v_rcp_f32_e32 v19, v17
	v_mul_f32_e32 v12, 0xbd38aa3b, v12
	v_mul_f32_e32 v13, 0xbd38aa3b, v13
	v_exp_f32_e32 v12, v12
	v_exp_f32_e32 v13, v13
	global_store_dwordx2 v[24:25], v[28:29], off
	v_cvt_pk_bf16_f32 v17, v22, v23
	global_store_dwordx2 v[24:25], v[16:17], off offset:1024
	v_cvt_pk_bf16_f32 v16, v20, v21
	v_cvt_pk_bf16_f32 v17, v18, v19
	v_mul_f32_e32 v8, 0xbd38aa3b, v8
	global_store_dwordx2 v[24:25], v[16:17], off offset:1536
	v_exp_f32_e32 v16, v8
	v_mul_f32_e32 v8, 0xbd38aa3b, v9
	v_add_f32_e32 v12, 1.0, v12
	v_add_f32_e32 v13, 1.0, v13
	v_mul_f32_e32 v14, 0xbd38aa3b, v14
	v_mul_f32_e32 v15, 0xbd38aa3b, v15
	v_exp_f32_e32 v9, v8
	v_mul_f32_e32 v10, 0xbd38aa3b, v10
	v_rcp_f32_e32 v12, v12
	v_exp_f32_e32 v14, v14
	v_exp_f32_e32 v15, v15
	v_rcp_f32_e32 v13, v13
	v_exp_f32_e32 v10, v10
	v_mul_f32_e32 v11, 0xbd38aa3b, v11
	v_exp_f32_e32 v11, v11
	v_add_f32_e32 v9, 1.0, v9
	v_add_f32_e32 v14, 1.0, v14
	v_add_f32_e32 v15, 1.0, v15
	v_cvt_pk_bf16_f32 v8, v12, v13
	v_rcp_f32_e32 v13, v9
	v_add_f32_e32 v9, 1.0, v10
	v_rcp_f32_e32 v14, v14
	v_rcp_f32_e32 v15, v15
	v_add_f32_e32 v12, 1.0, v16
	v_rcp_f32_e32 v10, v9
	v_add_f32_e32 v9, 1.0, v11
	v_rcp_f32_e32 v12, v12
	v_rcp_f32_e32 v11, v9
	v_mul_f32_e32 v4, 0xbd38aa3b, v4
	v_mul_f32_e32 v5, 0xbd38aa3b, v5
	v_exp_f32_e32 v4, v4
	v_exp_f32_e32 v5, v5
	v_cvt_pk_bf16_f32 v9, v14, v15
	global_store_dwordx2 v[24:25], v[8:9], off offset:2048
	v_cvt_pk_bf16_f32 v8, v12, v13
	v_cvt_pk_bf16_f32 v9, v10, v11
	v_mul_f32_e32 v0, 0xbd38aa3b, v0
	global_store_dwordx2 v[24:25], v[8:9], off offset:2560
	v_exp_f32_e32 v8, v0
	v_mul_f32_e32 v0, 0xbd38aa3b, v1
	v_add_f32_e32 v4, 1.0, v4
	v_add_f32_e32 v5, 1.0, v5
	v_mul_f32_e32 v6, 0xbd38aa3b, v6
	v_mul_f32_e32 v7, 0xbd38aa3b, v7
	v_exp_f32_e32 v1, v0
	v_mul_f32_e32 v2, 0xbd38aa3b, v2
	v_rcp_f32_e32 v4, v4
	v_exp_f32_e32 v6, v6
	v_exp_f32_e32 v7, v7
	v_rcp_f32_e32 v5, v5
	v_exp_f32_e32 v2, v2
	v_mul_f32_e32 v3, 0xbd38aa3b, v3
	v_exp_f32_e32 v3, v3
	v_add_f32_e32 v1, 1.0, v1
	v_add_f32_e32 v6, 1.0, v6
	v_add_f32_e32 v7, 1.0, v7
	v_cvt_pk_bf16_f32 v0, v4, v5
	v_rcp_f32_e32 v5, v1
	v_add_f32_e32 v1, 1.0, v2
	v_rcp_f32_e32 v6, v6
	v_rcp_f32_e32 v7, v7
	v_add_f32_e32 v4, 1.0, v8
	v_rcp_f32_e32 v2, v1
	v_add_f32_e32 v1, 1.0, v3
	v_rcp_f32_e32 v4, v4
	v_rcp_f32_e32 v3, v1
	v_cvt_pk_bf16_f32 v1, v6, v7
	global_store_dwordx2 v[24:25], v[0:1], off offset:3072
	v_cvt_pk_bf16_f32 v0, v4, v5
	v_cvt_pk_bf16_f32 v1, v2, v3
	global_store_dwordx2 v[24:25], v[0:1], off offset:3584

;     __device__ __forceinline__ void operator()(const f32x4 (&acc)[2][2][4][2], const Unit& u, int wr, int wc, int fr, int fq) const {
;     ...
;             for (int ai = 0; ai < 2; ++ai) {
;                 u32x2 g[16], t[16];
; #pragma unroll
;                 for (int k = 0; k < 16; ++k) { g[k] = tg[(ai * 16 + k) * 64]; if (mode != 1) t[k] = tm[(ai * 16 + k) * 64]; }
.LBB0_678:
	global_load_dwordx2 v[170:171], v[136:137], off offset:512
	global_load_dwordx2 v[200:201], v[134:135], off offset:1024
	s_and_b64 vcc, exec, s[8:9]
	s_cbranch_vccnz .LBB0_547
.LBB0_679:
	global_load_dwordx2 v[168:169], v[136:137], off offset:1024
	global_load_dwordx2 v[196:197], v[134:135], off offset:1536
	s_and_b64 vcc, exec, s[8:9]
	s_cbranch_vccnz .LBB0_548
.LBB0_680:
	global_load_dwordx2 v[166:167], v[136:137], off offset:1536
	global_load_dwordx2 v[198:199], v[134:135], off offset:2048
	s_and_b64 vcc, exec, s[8:9]
	s_cbranch_vccnz .LBB0_549
.LBB0_681:
	global_load_dwordx2 v[164:165], v[136:137], off offset:2048
	global_load_dwordx2 v[194:195], v[134:135], off offset:2560
	s_and_b64 vcc, exec, s[8:9]
	s_cbranch_vccnz .LBB0_550
.LBB0_682:
	global_load_dwordx2 v[162:163], v[136:137], off offset:2560
	global_load_dwordx2 v[192:193], v[134:135], off offset:3072
	s_and_b64 vcc, exec, s[8:9]
	s_cbranch_vccnz .LBB0_551
.LBB0_683:
	global_load_dwordx2 v[160:161], v[136:137], off offset:3072
	global_load_dwordx2 v[190:191], v[134:135], off offset:3584
	s_and_b64 vcc, exec, s[8:9]
	s_cbranch_vccz .LBB0_552
	s_branch .LBB0_553

; __device__ __forceinline__ u32x2 pk4(f32x4 v) { u32x2 w; w.x = pk2(v[0], v[1]); w.y = pk2(v[2], v[3]); return w; }
;     __device__ __forceinline__ void operator()(const f32x4 (&acc)[2][2][4][2], const Unit& u, int wr, int wc, int fr, int fq) const {
;     ...
; #pragma unroll
;                 for (int bj = 0; bj < 2; ++bj)
; #pragma unroll
;                     for (int m = 0; m < 4; ++m) { const int k = (bj * 4 + m) * 2;
;                         f32x4 v0 = unpk4(g[k]) * (acc[ai][bj][m][0] * (1.0f / 512.0f)), v1 = unpk4(g[k + 1]) * (acc[ai][bj][m][1] * (1.0f / 512.0f));
;                         if (mode != 1) { v0 += unpk4(t[k]); v1 += unpk4(t[k + 1]); }
;                         if (mode != 3) { tm[(ai * 16 + k) * 64] = pk4(v0); tm[(ai * 16 + k + 1) * 64] = pk4(v1); }
.LBB0_685:
	v_cvt_pk_bf16_f32 v194, v200, v201
	v_cvt_pk_bf16_f32 v195, v198, v199
	global_store_dwordx2 v[136:137], v[194:195], off offset:2048
	v_cvt_pk_bf16_f32 v194, v204, v205
	v_cvt_pk_bf16_f32 v195, v202, v203
	global_store_dwordx2 v[136:137], v[194:195], off offset:2560
	v_or_b32_e32 v194, 32, v144
	v_ashrrev_i32_e32 v195, 31, v194
	s_cbranch_execz .LBB0_584
	s_branch .LBB0_585

; __device__ __forceinline__ u32x2 pk4(f32x4 v) { u32x2 w; w.x = pk2(v[0], v[1]); w.y = pk2(v[2], v[3]); return w; }
;     __device__ __forceinline__ void operator()(const f32x4 (&acc)[2][2][4][2], const Unit& u, int wr, int wc, int fr, int fq) const {
;     ...
; #pragma unroll
;                 for (int bj = 0; bj < 2; ++bj)
; #pragma unroll
;                     for (int m = 0; m < 4; ++m) { const int k = (bj * 4 + m) * 2;
;                         f32x4 v0 = unpk4(g[k]) * (acc[ai][bj][m][0] * (1.0f / 512.0f)), v1 = unpk4(g[k + 1]) * (acc[ai][bj][m][1] * (1.0f / 512.0f));
;                         if (mode != 1) { v0 += unpk4(t[k]); v1 += unpk4(t[k + 1]); }
;                         if (mode != 3) { tm[(ai * 16 + k) * 64] = pk4(v0); tm[(ai * 16 + k + 1) * 64] = pk4(v1); }
.LBB0_687:
	v_cvt_pk_bf16_f32 v190, v198, v199
	v_cvt_pk_bf16_f32 v191, v192, v193
	global_store_dwordx2 v[136:137], v[190:191], off offset:3072
	v_cvt_pk_bf16_f32 v190, v202, v203
	v_cvt_pk_bf16_f32 v191, v200, v201
	global_store_dwordx2 v[136:137], v[190:191], off offset:3584
	v_or_b32_e32 v190, 48, v144
	v_ashrrev_i32_e32 v191, 31, v190
	s_cbranch_execz .LBB0_588
	s_branch .LBB0_589

; __device__ __forceinline__ u32x2 pk4(f32x4 v) { u32x2 w; w.x = pk2(v[0], v[1]); w.y = pk2(v[2], v[3]); return w; }
;     __device__ __forceinline__ void operator()(const f32x4 (&acc)[2][2][4][2], const Unit& u, int wr, int wc, int fr, int fq) const {
;     ...
; #pragma unroll
;                 for (int bj = 0; bj < 2; ++bj)
; #pragma unroll
;                     for (int m = 0; m < 4; ++m) { const int k = (bj * 4 + m) * 2;
;                         f32x4 v0 = unpk4(g[k]) * (acc[ai][bj][m][0] * (1.0f / 512.0f)), v1 = unpk4(g[k + 1]) * (acc[ai][bj][m][1] * (1.0f / 512.0f));
;                         if (mode != 1) { v0 += unpk4(t[k]); v1 += unpk4(t[k + 1]); }
;                         if (mode != 3) { tm[(ai * 16 + k) * 64] = pk4(v0); tm[(ai * 16 + k + 1) * 64] = pk4(v1); }
.LBB0_689:
	v_add_co_u32_e32 v202, vcc, 0x1000, v136
	v_cvt_pk_bf16_f32 v200, v192, v193
	v_cvt_pk_bf16_f32 v201, v186, v187
	v_addc_co_u32_e32 v203, vcc, 0, v137, vcc
	global_store_dwordx2 v[202:203], v[200:201], off
	v_cvt_pk_bf16_f32 v200, v198, v199
	v_cvt_pk_bf16_f32 v201, v188, v189
	global_store_dwordx2 v[202:203], v[200:201], off offset:512
	s_cbranch_execz .LBB0_592
	s_branch .LBB0_593

; __device__ __forceinline__ u32x2 pk4(f32x4 v) { u32x2 w; w.x = pk2(v[0], v[1]); w.y = pk2(v[2], v[3]); return w; }
;     __device__ __forceinline__ void operator()(const f32x4 (&acc)[2][2][4][2], const Unit& u, int wr, int wc, int fr, int fq) const {
;     ...
; #pragma unroll
;                 for (int bj = 0; bj < 2; ++bj)
; #pragma unroll
;                     for (int m = 0; m < 4; ++m) { const int k = (bj * 4 + m) * 2;
;                         f32x4 v0 = unpk4(g[k]) * (acc[ai][bj][m][0] * (1.0f / 512.0f)), v1 = unpk4(g[k + 1]) * (acc[ai][bj][m][1] * (1.0f / 512.0f));
;                         if (mode != 1) { v0 += unpk4(t[k]); v1 += unpk4(t[k + 1]); }
;                         if (mode != 3) { tm[(ai * 16 + k) * 64] = pk4(v0); tm[(ai * 16 + k + 1) * 64] = pk4(v1); }
.LBB0_691:
	v_add_co_u32_e32 v198, vcc, 0x1000, v136
	v_cvt_pk_bf16_f32 v192, v186, v187
	v_cvt_pk_bf16_f32 v193, v182, v183
	v_addc_co_u32_e32 v199, vcc, 0, v137, vcc
	global_store_dwordx2 v[198:199], v[192:193], off offset:1024
	v_cvt_pk_bf16_f32 v192, v188, v189
	v_cvt_pk_bf16_f32 v193, v184, v185
	global_store_dwordx2 v[198:199], v[192:193], off offset:1536
	s_cbranch_execz .LBB0_596
	s_branch .LBB0_597

; __device__ __forceinline__ u32x2 pk4(f32x4 v) { u32x2 w; w.x = pk2(v[0], v[1]); w.y = pk2(v[2], v[3]); return w; }
;     __device__ __forceinline__ void operator()(const f32x4 (&acc)[2][2][4][2], const Unit& u, int wr, int wc, int fr, int fq) const {
;     ...
; #pragma unroll
;                 for (int bj = 0; bj < 2; ++bj)
; #pragma unroll
;                     for (int m = 0; m < 4; ++m) { const int k = (bj * 4 + m) * 2;
;                         f32x4 v0 = unpk4(g[k]) * (acc[ai][bj][m][0] * (1.0f / 512.0f)), v1 = unpk4(g[k + 1]) * (acc[ai][bj][m][1] * (1.0f / 512.0f));
;                         if (mode != 1) { v0 += unpk4(t[k]); v1 += unpk4(t[k + 1]); }
;                         if (mode != 3) { tm[(ai * 16 + k) * 64] = pk4(v0); tm[(ai * 16 + k + 1) * 64] = pk4(v1); }
.LBB0_693:
	v_add_co_u32_e32 v188, vcc, 0x1000, v136
	v_cvt_pk_bf16_f32 v186, v182, v183
	v_cvt_pk_bf16_f32 v187, v178, v179
	v_addc_co_u32_e32 v189, vcc, 0, v137, vcc
	global_store_dwordx2 v[188:189], v[186:187], off offset:2048
	v_cvt_pk_bf16_f32 v186, v184, v185
	v_cvt_pk_bf16_f32 v187, v180, v181
	global_store_dwordx2 v[188:189], v[186:187], off offset:2560
	s_cbranch_execz .LBB0_600
	s_branch .LBB0_601

; __device__ __forceinline__ u32x2 pk4(f32x4 v) { u32x2 w; w.x = pk2(v[0], v[1]); w.y = pk2(v[2], v[3]); return w; }
;     __device__ __forceinline__ void operator()(const f32x4 (&acc)[2][2][4][2], const Unit& u, int wr, int wc, int fr, int fq) const {
;     ...
; #pragma unroll
;                 for (int bj = 0; bj < 2; ++bj)
; #pragma unroll
;                     for (int m = 0; m < 4; ++m) { const int k = (bj * 4 + m) * 2;
;                         f32x4 v0 = unpk4(g[k]) * (acc[ai][bj][m][0] * (1.0f / 512.0f)), v1 = unpk4(g[k + 1]) * (acc[ai][bj][m][1] * (1.0f / 512.0f));
;                         if (mode != 1) { v0 += unpk4(t[k]); v1 += unpk4(t[k + 1]); }
;                         if (mode != 3) { tm[(ai * 16 + k) * 64] = pk4(v0); tm[(ai * 16 + k + 1) * 64] = pk4(v1); }
.LBB0_695:
	v_add_co_u32_e32 v184, vcc, 0x1000, v136
	v_cvt_pk_bf16_f32 v182, v178, v179
	v_cvt_pk_bf16_f32 v183, v174, v175
	v_addc_co_u32_e32 v185, vcc, 0, v137, vcc
	global_store_dwordx2 v[184:185], v[182:183], off offset:3072
	v_cvt_pk_bf16_f32 v182, v180, v181
	v_cvt_pk_bf16_f32 v183, v176, v177
	global_store_dwordx2 v[184:185], v[182:183], off offset:3584
	s_cbranch_execz .LBB0_604
	s_branch .LBB0_605

; __device__ __forceinline__ u32x2 pk4(f32x4 v) { u32x2 w; w.x = pk2(v[0], v[1]); w.y = pk2(v[2], v[3]); return w; }
;     __device__ __forceinline__ void operator()(const f32x4 (&acc)[2][2][4][2], const Unit& u, int wr, int wc, int fr, int fq) const {
;     ...
; #pragma unroll
;                 for (int bj = 0; bj < 2; ++bj)
; #pragma unroll
;                     for (int m = 0; m < 4; ++m) { const int k = (bj * 4 + m) * 2;
;                         f32x4 v0 = unpk4(g[k]) * (acc[ai][bj][m][0] * (1.0f / 512.0f)), v1 = unpk4(g[k + 1]) * (acc[ai][bj][m][1] * (1.0f / 512.0f));
;                         if (mode != 1) { v0 += unpk4(t[k]); v1 += unpk4(t[k + 1]); }
;                         if (mode != 3) { tm[(ai * 16 + k) * 64] = pk4(v0); tm[(ai * 16 + k + 1) * 64] = pk4(v1); }
.LBB0_697:
	v_add_co_u32_e32 v172, vcc, 0x2000, v136
	v_cvt_pk_bf16_f32 v170, v206, v207
	v_cvt_pk_bf16_f32 v171, v202, v203
	v_addc_co_u32_e32 v173, vcc, 0, v137, vcc
	global_store_dwordx2 v[172:173], v[170:171], off
	v_cvt_pk_bf16_f32 v170, v208, v209
	v_cvt_pk_bf16_f32 v171, v204, v205
	global_store_dwordx2 v[172:173], v[170:171], off offset:512
	v_add_u32_e32 v170, 0x80, v144
	v_ashrrev_i32_e32 v171, 31, v170
	s_cbranch_execz .LBB0_640
	s_branch .LBB0_641

; __device__ __forceinline__ u32x2 pk4(f32x4 v) { u32x2 w; w.x = pk2(v[0], v[1]); w.y = pk2(v[2], v[3]); return w; }
;     __device__ __forceinline__ void operator()(const f32x4 (&acc)[2][2][4][2], const Unit& u, int wr, int wc, int fr, int fq) const {
;     ...
; #pragma unroll
;                 for (int bj = 0; bj < 2; ++bj)
; #pragma unroll
;                     for (int m = 0; m < 4; ++m) { const int k = (bj * 4 + m) * 2;
;                         f32x4 v0 = unpk4(g[k]) * (acc[ai][bj][m][0] * (1.0f / 512.0f)), v1 = unpk4(g[k + 1]) * (acc[ai][bj][m][1] * (1.0f / 512.0f));
;                         if (mode != 1) { v0 += unpk4(t[k]); v1 += unpk4(t[k + 1]); }
;                         if (mode != 3) { tm[(ai * 16 + k) * 64] = pk4(v0); tm[(ai * 16 + k + 1) * 64] = pk4(v1); }
.LBB0_699:
	v_add_co_u32_e32 v168, vcc, 0x2000, v136
	v_cvt_pk_bf16_f32 v166, v198, v199
	v_cvt_pk_bf16_f32 v167, v172, v173
	v_addc_co_u32_e32 v169, vcc, 0, v137, vcc
	global_store_dwordx2 v[168:169], v[166:167], off offset:1024
	v_cvt_pk_bf16_f32 v166, v202, v203
	v_cvt_pk_bf16_f32 v167, v200, v201
	global_store_dwordx2 v[168:169], v[166:167], off offset:1536
	s_cbranch_execz .LBB0_644
	s_branch .LBB0_645

; __device__ __forceinline__ u32x2 pk4(f32x4 v) { u32x2 w; w.x = pk2(v[0], v[1]); w.y = pk2(v[2], v[3]); return w; }
;     __device__ __forceinline__ void operator()(const f32x4 (&acc)[2][2][4][2], const Unit& u, int wr, int wc, int fr, int fq) const {
;     ...
; #pragma unroll
;                 for (int bj = 0; bj < 2; ++bj)
; #pragma unroll
;                     for (int m = 0; m < 4; ++m) { const int k = (bj * 4 + m) * 2;
;                         f32x4 v0 = unpk4(g[k]) * (acc[ai][bj][m][0] * (1.0f / 512.0f)), v1 = unpk4(g[k + 1]) * (acc[ai][bj][m][1] * (1.0f / 512.0f));
;                         if (mode != 1) { v0 += unpk4(t[k]); v1 += unpk4(t[k + 1]); }
;                         if (mode != 3) { tm[(ai * 16 + k) * 64] = pk4(v0); tm[(ai * 16 + k + 1) * 64] = pk4(v1); }
.LBB0_701:
	v_add_co_u32_e32 v164, vcc, 0x2000, v136
	v_cvt_pk_bf16_f32 v162, v168, v169
	v_cvt_pk_bf16_f32 v163, v166, v167
	v_addc_co_u32_e32 v165, vcc, 0, v137, vcc
	global_store_dwordx2 v[164:165], v[162:163], off offset:2048
	v_cvt_pk_bf16_f32 v162, v194, v195
	v_cvt_pk_bf16_f32 v163, v172, v173
	global_store_dwordx2 v[164:165], v[162:163], off offset:2560
	s_cbranch_execz .LBB0_648
	s_branch .LBB0_649

; __device__ __forceinline__ u32x2 pk4(f32x4 v) { u32x2 w; w.x = pk2(v[0], v[1]); w.y = pk2(v[2], v[3]); return w; }
;     __device__ __forceinline__ void operator()(const f32x4 (&acc)[2][2][4][2], const Unit& u, int wr, int wc, int fr, int fq) const {
;     ...
; #pragma unroll
;                 for (int bj = 0; bj < 2; ++bj)
; #pragma unroll
;                     for (int m = 0; m < 4; ++m) { const int k = (bj * 4 + m) * 2;
;                         f32x4 v0 = unpk4(g[k]) * (acc[ai][bj][m][0] * (1.0f / 512.0f)), v1 = unpk4(g[k + 1]) * (acc[ai][bj][m][1] * (1.0f / 512.0f));
;                         if (mode != 1) { v0 += unpk4(t[k]); v1 += unpk4(t[k + 1]); }
;                         if (mode != 3) { tm[(ai * 16 + k) * 64] = pk4(v0); tm[(ai * 16 + k + 1) * 64] = pk4(v1); }
.LBB0_703:
	v_add_co_u32_e32 v160, vcc, 0x2000, v136
	v_cvt_pk_bf16_f32 v158, v164, v165
	v_cvt_pk_bf16_f32 v159, v162, v163
	v_addc_co_u32_e32 v161, vcc, 0, v137, vcc
	global_store_dwordx2 v[160:161], v[158:159], off offset:3072
	v_cvt_pk_bf16_f32 v158, v168, v169
	v_cvt_pk_bf16_f32 v159, v166, v167
	global_store_dwordx2 v[160:161], v[158:159], off offset:3584
	s_cbranch_execz .LBB0_652
	s_branch .LBB0_653

; __device__ __forceinline__ u32x2 pk4(f32x4 v) { u32x2 w; w.x = pk2(v[0], v[1]); w.y = pk2(v[2], v[3]); return w; }
;     __device__ __forceinline__ void operator()(const f32x4 (&acc)[2][2][4][2], const Unit& u, int wr, int wc, int fr, int fq) const {
;     ...
; #pragma unroll
;                 for (int bj = 0; bj < 2; ++bj)
; #pragma unroll
;                     for (int m = 0; m < 4; ++m) { const int k = (bj * 4 + m) * 2;
;                         f32x4 v0 = unpk4(g[k]) * (acc[ai][bj][m][0] * (1.0f / 512.0f)), v1 = unpk4(g[k + 1]) * (acc[ai][bj][m][1] * (1.0f / 512.0f));
;                         if (mode != 1) { v0 += unpk4(t[k]); v1 += unpk4(t[k + 1]); }
;                         if (mode != 3) { tm[(ai * 16 + k) * 64] = pk4(v0); tm[(ai * 16 + k + 1) * 64] = pk4(v1); }
.LBB0_705:
	v_add_co_u32_e32 v156, vcc, 0x3000, v136
	v_cvt_pk_bf16_f32 v154, v160, v161
	v_cvt_pk_bf16_f32 v155, v158, v159
	v_addc_co_u32_e32 v157, vcc, 0, v137, vcc
	global_store_dwordx2 v[156:157], v[154:155], off
	v_cvt_pk_bf16_f32 v154, v164, v165
	v_cvt_pk_bf16_f32 v155, v162, v163
	global_store_dwordx2 v[156:157], v[154:155], off offset:512
	s_cbranch_execz .LBB0_656
	s_branch .LBB0_657

; __device__ __forceinline__ u32x2 pk4(f32x4 v) { u32x2 w; w.x = pk2(v[0], v[1]); w.y = pk2(v[2], v[3]); return w; }
;     __device__ __forceinline__ void operator()(const f32x4 (&acc)[2][2][4][2], const Unit& u, int wr, int wc, int fr, int fq) const {
;     ...
; #pragma unroll
;                 for (int bj = 0; bj < 2; ++bj)
; #pragma unroll
;                     for (int m = 0; m < 4; ++m) { const int k = (bj * 4 + m) * 2;
;                         f32x4 v0 = unpk4(g[k]) * (acc[ai][bj][m][0] * (1.0f / 512.0f)), v1 = unpk4(g[k + 1]) * (acc[ai][bj][m][1] * (1.0f / 512.0f));
;                         if (mode != 1) { v0 += unpk4(t[k]); v1 += unpk4(t[k + 1]); }
;                         if (mode != 3) { tm[(ai * 16 + k) * 64] = pk4(v0); tm[(ai * 16 + k + 1) * 64] = pk4(v1); }
.LBB0_707:
	v_add_co_u32_e32 v152, vcc, 0x3000, v136
	v_cvt_pk_bf16_f32 v150, v156, v157
	v_cvt_pk_bf16_f32 v151, v154, v155
	v_addc_co_u32_e32 v153, vcc, 0, v137, vcc
	global_store_dwordx2 v[152:153], v[150:151], off offset:1024
	v_cvt_pk_bf16_f32 v150, v160, v161
	v_cvt_pk_bf16_f32 v151, v158, v159
	global_store_dwordx2 v[152:153], v[150:151], off offset:1536
	s_cbranch_execz .LBB0_660
	s_branch .LBB0_661

; __device__ __forceinline__ u32x2 pk4(f32x4 v) { u32x2 w; w.x = pk2(v[0], v[1]); w.y = pk2(v[2], v[3]); return w; }
;     __device__ __forceinline__ void operator()(const f32x4 (&acc)[2][2][4][2], const Unit& u, int wr, int wc, int fr, int fq) const {
;     ...
; #pragma unroll
;                 for (int bj = 0; bj < 2; ++bj)
; #pragma unroll
;                     for (int m = 0; m < 4; ++m) { const int k = (bj * 4 + m) * 2;
;                         f32x4 v0 = unpk4(g[k]) * (acc[ai][bj][m][0] * (1.0f / 512.0f)), v1 = unpk4(g[k + 1]) * (acc[ai][bj][m][1] * (1.0f / 512.0f));
;                         if (mode != 1) { v0 += unpk4(t[k]); v1 += unpk4(t[k + 1]); }
;                         if (mode != 3) { tm[(ai * 16 + k) * 64] = pk4(v0); tm[(ai * 16 + k + 1) * 64] = pk4(v1); }
.LBB0_709:
	v_add_co_u32_e32 v148, vcc, 0x3000, v136
	v_cvt_pk_bf16_f32 v146, v152, v153
	v_cvt_pk_bf16_f32 v147, v150, v151
	v_addc_co_u32_e32 v149, vcc, 0, v137, vcc
	global_store_dwordx2 v[148:149], v[146:147], off offset:2048
	v_cvt_pk_bf16_f32 v146, v156, v157
	v_cvt_pk_bf16_f32 v147, v154, v155
	global_store_dwordx2 v[148:149], v[146:147], off offset:2560
	s_cbranch_execz .LBB0_664
	s_branch .LBB0_665

; __device__ __forceinline__ u32x2 pk4(f32x4 v) { u32x2 w; w.x = pk2(v[0], v[1]); w.y = pk2(v[2], v[3]); return w; }
;     __device__ __forceinline__ void operator()(const f32x4 (&acc)[2][2][4][2], const Unit& u, int wr, int wc, int fr, int fq) const {
;     ...
; #pragma unroll
;                 for (int bj = 0; bj < 2; ++bj)
; #pragma unroll
;                     for (int m = 0; m < 4; ++m) { const int k = (bj * 4 + m) * 2;
;                         f32x4 v0 = unpk4(g[k]) * (acc[ai][bj][m][0] * (1.0f / 512.0f)), v1 = unpk4(g[k + 1]) * (acc[ai][bj][m][1] * (1.0f / 512.0f));
;                         if (mode != 1) { v0 += unpk4(t[k]); v1 += unpk4(t[k + 1]); }
;                         if (mode != 3) { tm[(ai * 16 + k) * 64] = pk4(v0); tm[(ai * 16 + k + 1) * 64] = pk4(v1); }
.LBB0_711:
	v_add_co_u32_e32 v136, vcc, 0x3000, v136
	v_cvt_pk_bf16_f32 v138, v148, v149
	v_cvt_pk_bf16_f32 v139, v146, v147
	v_addc_co_u32_e32 v137, vcc, 0, v137, vcc
	global_store_dwordx2 v[136:137], v[138:139], off offset:3072
	v_cvt_pk_bf16_f32 v138, v152, v153
	v_cvt_pk_bf16_f32 v139, v150, v151
	global_store_dwordx2 v[136:137], v[138:139], off offset:3584
	s_cbranch_execz .LBB0_668
	s_branch .LBB0_669
